# GQA loop: post-barrier softmax work deferred into next scheduling region (QK accumulator chains run back to back), first-iteration copy of the region
# speedup vs baseline: 1.0035x; 1.0035x over previous
.LBB0_739:
	ds_read_b128 v[236:239], v200 offset:49152
	ds_read_b128 v[240:243], v208 offset:49152
	ds_read_b128 v[244:247], v207 offset:49152
	ds_read_b128 v[248:251], v206 offset:49152
	s_add_i32 s6, s14, -3
	s_waitcnt lgkmcnt(3)
	v_mfma_f32_32x32x16_bf16 v[80:95], v[236:239], v[124:127], 0
	ds_read_b128 v[236:239], v205 offset:49152
	v_exp_f32_e32 v158, v158
	v_exp_f32_e32 v159, v159
	v_add_f32_e32 v210, 0, v162
	s_waitcnt lgkmcnt(3)
	v_mfma_f32_32x32x16_bf16 v[80:95], v[240:243], v[120:123], v[80:95]
	ds_read_b128 v[240:243], v204 offset:49152
	v_exp_f32_e32 v156, v156
	v_exp_f32_e32 v157, v157
	v_add_f32_e32 v210, v216, v210
	s_waitcnt lgkmcnt(3)
	v_mfma_f32_32x32x16_bf16 v[80:95], v[244:247], v[116:119], v[80:95]
	ds_read_b128 v[244:247], v202 offset:49152
	v_exp_f32_e32 v150, v150
	v_exp_f32_e32 v151, v151
	v_add_f32_e32 v210, v163, v210
	s_waitcnt lgkmcnt(3)
	v_mfma_f32_32x32x16_bf16 v[80:95], v[248:251], v[112:115], v[80:95]
	ds_read_b128 v[248:251], v201 offset:49152
	v_exp_f32_e32 v148, v148
	v_exp_f32_e32 v149, v149
	v_add_f32_e32 v210, v177, v210
	s_waitcnt lgkmcnt(3)
	v_mfma_f32_32x32x16_bf16 v[80:95], v[236:239], v[108:111], v[80:95]
	ds_read_b128 v[236:239], v200 offset:57344
	v_exp_f32_e32 v146, v146
	v_exp_f32_e32 v147, v147
	v_add_f32_e32 v210, v164, v210
	s_waitcnt lgkmcnt(3)
	v_mfma_f32_32x32x16_bf16 v[80:95], v[240:243], v[104:107], v[80:95]
	ds_read_b128 v[240:243], v208 offset:57344
	v_exp_f32_e32 v160, v160
	v_exp_f32_e32 v161, v161
	v_add_f32_e32 v210, v176, v210
	s_waitcnt lgkmcnt(3)
	v_mfma_f32_32x32x16_bf16 v[80:95], v[244:247], v[100:103], v[80:95]
	ds_read_b128 v[244:247], v207 offset:57344
	v_exp_f32_e32 v154, v154
	v_exp_f32_e32 v155, v155
	v_add_f32_e32 v210, v165, v210
	s_waitcnt lgkmcnt(3)
	v_mfma_f32_32x32x16_bf16 v[80:95], v[248:251], v[96:99], v[80:95]
	ds_read_b128 v[248:251], v206 offset:57344
	v_exp_f32_e32 v152, v152
	v_exp_f32_e32 v153, v153
	v_add_f32_e32 v210, v175, v210
	s_waitcnt lgkmcnt(3)
	v_mfma_f32_32x32x16_bf16 v[64:79], v[236:239], v[124:127], 0
	ds_read_b128 v[236:239], v205 offset:57344
	v_add_f32_e32 v210, v166, v210
	v_add_f32_e32 v210, v173, v210
	v_add_f32_e32 v210, v167, v210
	v_add_f32_e32 v210, v172, v210
	v_add_f32_e32 v210, v168, v210
	s_waitcnt lgkmcnt(3)
	v_mfma_f32_32x32x16_bf16 v[64:79], v[240:243], v[120:123], v[64:79]
	ds_read_b128 v[240:243], v204 offset:57344
	v_add_f32_e32 v210, v171, v210
	v_add_f32_e32 v210, v169, v210
	v_add_f32_e32 v210, v170, v210
	v_add_f32_e32 v210, v158, v210
	v_add_f32_e32 v210, v159, v210
	s_waitcnt lgkmcnt(3)
	v_mfma_f32_32x32x16_bf16 v[64:79], v[244:247], v[116:119], v[64:79]
	ds_read_b128 v[244:247], v202 offset:57344
	v_add_f32_e32 v210, v156, v210
	v_add_f32_e32 v210, v157, v210
	v_add_f32_e32 v210, v150, v210
	v_add_f32_e32 v210, v151, v210
	v_add_f32_e32 v210, v148, v210
	s_waitcnt lgkmcnt(3)
	v_mfma_f32_32x32x16_bf16 v[64:79], v[248:251], v[112:115], v[64:79]
	ds_read_b128 v[248:251], v201 offset:57344
	v_add_f32_e32 v210, v149, v210
	v_add_f32_e32 v210, v146, v210
	v_add_f32_e32 v210, v147, v210
	v_add_f32_e32 v210, v160, v210
	v_add_f32_e32 v210, v161, v210
	s_waitcnt lgkmcnt(3)
	v_mfma_f32_32x32x16_bf16 v[64:79], v[236:239], v[108:111], v[64:79]
	v_add_f32_e32 v210, v154, v210
	v_add_f32_e32 v210, v155, v210
	v_add_f32_e32 v210, v152, v210
	v_add_f32_e32 v210, v153, v210
	v_mov_b32_e32 v211, v210
	s_waitcnt lgkmcnt(2)
	v_mfma_f32_32x32x16_bf16 v[64:79], v[240:243], v[104:107], v[64:79]
	v_cvt_pk_bf16_f32 v162, v162, v216
	v_cvt_pk_bf16_f32 v163, v163, v177
	v_cvt_pk_bf16_f32 v164, v164, v176
	v_permlane32_swap_b32_e32 v210, v211
	v_cvt_pk_bf16_f32 v165, v165, v175
	ds_read_b64_tr_b16 v[216:217], v193 offset:0
	ds_read_b64_tr_b16 v[218:219], v193 offset:0x800
	ds_read_b64_tr_b16 v[220:221], v193 offset:0x1000
	ds_read_b64_tr_b16 v[222:223], v193 offset:0x1800
	ds_read_b64_tr_b16 v[224:225], v193 offset:0x2000
	ds_read_b64_tr_b16 v[226:227], v193 offset:0x2800
	ds_read_b64_tr_b16 v[232:233], v193 offset:0x3000
	ds_read_b64_tr_b16 v[234:235], v193 offset:0x3800
	s_waitcnt lgkmcnt(9)
	v_mfma_f32_32x32x16_bf16 v[64:79], v[244:247], v[100:103], v[64:79]
	v_permlane32_swap_b32_e32 v162, v164
	v_cvt_pk_bf16_f32 v166, v166, v173
	v_cvt_pk_bf16_f32 v167, v167, v172
	v_cvt_pk_bf16_f32 v168, v168, v171
	v_cvt_pk_bf16_f32 v169, v169, v170
	s_waitcnt lgkmcnt(8)
	v_mfma_f32_32x32x16_bf16 v[64:79], v[248:251], v[96:99], v[64:79]
	v_cvt_pk_bf16_f32 v170, v158, v159
	v_cvt_pk_bf16_f32 v171, v156, v157
	v_cvt_pk_bf16_f32 v172, v150, v151
	v_cvt_pk_bf16_f32 v173, v148, v149
	v_cvt_pk_bf16_f32 v212, v146, v147
	s_waitcnt vmcnt(0)
	ds_write_b128 v198, v[136:139] offset:32768
	ds_write_b128 v199, v[140:143] offset:32768
	s_sub_i32 s7, s8, 64
	s_cmp_lt_u32 s6, 2
	s_cselect_b32 s6, s15, s7
	s_ashr_i32 s7, s6, 31
	v_permlane32_swap_b32_e32 v163, v165
	s_waitcnt lgkmcnt(8)
	s_nop 0
	v_mfma_f32_32x32x16_bf16 v[48:63], v[162:165], v[216:219], v[48:63]
	ds_read_b64_tr_b16 v[216:217], v193 offset:0x200
	ds_read_b64_tr_b16 v[218:219], v193 offset:0xa00
	v_cvt_pk_bf16_f32 v213, v160, v161
	v_cvt_pk_bf16_f32 v214, v154, v155
	v_cvt_pk_bf16_f32 v215, v152, v153
	v_permlane32_swap_b32_e32 v166, v168
	v_permlane32_swap_b32_e32 v167, v169
	s_waitcnt lgkmcnt(8)
	s_nop 0
	v_mfma_f32_32x32x16_bf16 v[48:63], v[166:169], v[220:223], v[48:63]
	ds_read_b64_tr_b16 v[220:221], v193 offset:0x1200
	ds_read_b64_tr_b16 v[222:223], v193 offset:0x1a00
	v_permlane32_swap_b32_e32 v170, v172
	v_permlane32_swap_b32_e32 v171, v173
	v_permlane32_swap_b32_e32 v212, v214
	v_permlane32_swap_b32_e32 v213, v215
	v_lshl_add_u64 v[146:147], s[6:7], 0, v[178:179]
	s_waitcnt lgkmcnt(8)
	v_mfma_f32_32x32x16_bf16 v[48:63], v[170:173], v[224:227], v[48:63]
	ds_read_b64_tr_b16 v[224:225], v193 offset:0x2200
	ds_read_b64_tr_b16 v[226:227], v193 offset:0x2a00
	v_mul_lo_u32 v148, v147, s40
	v_mul_lo_u32 v149, v146, s41
	v_mad_u64_u32 v[146:147], s[10:11], v146, s40, 0
	v_add3_u32 v147, v147, v149, v148
	v_lshl_add_u64 v[148:149], v[180:181], 0, s[6:7]
	s_waitcnt lgkmcnt(8)
	v_mfma_f32_32x32x16_bf16 v[48:63], v[212:215], v[232:235], v[48:63]
	ds_read_b64_tr_b16 v[232:233], v193 offset:0x3200
	ds_read_b64_tr_b16 v[234:235], v193 offset:0x3a00
	v_mul_lo_u32 v150, v149, s40
	v_mul_lo_u32 v151, v148, s41
	v_mad_u64_u32 v[148:149], s[6:7], v148, s40, 0
	v_add3_u32 v149, v149, v151, v150
	v_lshlrev_b64 v[154:155], 1, v[146:147]
	s_waitcnt lgkmcnt(6)
	v_mfma_f32_32x32x16_bf16 v[32:47], v[162:165], v[216:219], v[32:47]
	ds_read_b64_tr_b16 v[216:217], v193 offset:0x400
	ds_read_b64_tr_b16 v[218:219], v193 offset:0xc00
	v_lshlrev_b64 v[156:157], 1, v[148:149]
	v_lshl_add_u64 v[146:147], v[182:183], 0, v[154:155]
	v_lshl_add_u64 v[150:151], v[182:183], 0, v[156:157]
	v_lshl_add_u64 v[154:155], v[184:185], 0, v[154:155]
	v_lshl_add_u64 v[158:159], v[184:185], 0, v[156:157]
	s_waitcnt lgkmcnt(6)
	v_mfma_f32_32x32x16_bf16 v[32:47], v[166:169], v[220:223], v[32:47]
	ds_read_b64_tr_b16 v[220:221], v193 offset:0x1400
	ds_read_b64_tr_b16 v[222:223], v193 offset:0x1c00
	v_max_f32_e32 v250, v81, v81
	v_max_f32_e32 v251, v80, v80
	v_max_f32_e32 v250, v251, v250
	v_max3_f32 v250, v250, v82, v83
	v_max3_f32 v250, v250, v84, v85
	global_load_dwordx4 v[146:149], v[146:147], off
	global_load_dwordx4 v[150:153], v[150:151], off
	global_load_dwordx4 v[154:157], v[154:155], off
	global_load_dwordx4 v[158:161], v[158:159], off
	s_waitcnt lgkmcnt(6)
	v_mfma_f32_32x32x16_bf16 v[32:47], v[170:173], v[224:227], v[32:47]
	ds_read_b64_tr_b16 v[224:225], v193 offset:0x2400
	ds_read_b64_tr_b16 v[226:227], v193 offset:0x2c00
	v_max3_f32 v250, v250, v86, v87
	v_max3_f32 v250, v250, v88, v89
	v_max3_f32 v250, v250, v90, v91
	v_max3_f32 v250, v250, v92, v93
	v_max3_f32 v250, v250, v94, v95
	s_waitcnt lgkmcnt(6)
	v_mfma_f32_32x32x16_bf16 v[32:47], v[212:215], v[232:235], v[32:47]
	ds_read_b64_tr_b16 v[232:233], v193 offset:0x3400
	ds_read_b64_tr_b16 v[234:235], v193 offset:0x3c00
	v_max3_f32 v250, v250, v64, v65
	v_max3_f32 v250, v250, v66, v67
	v_max3_f32 v250, v250, v68, v69
	v_max3_f32 v250, v250, v70, v71
	v_max3_f32 v250, v250, v72, v73
	s_waitcnt lgkmcnt(6)
	v_mfma_f32_32x32x16_bf16 v[16:31], v[162:165], v[216:219], v[16:31]
	ds_read_b64_tr_b16 v[216:217], v193 offset:0x600
	ds_read_b64_tr_b16 v[218:219], v193 offset:0xe00
	v_max3_f32 v250, v250, v74, v75
	v_max3_f32 v250, v250, v76, v77
	v_max3_f32 v250, v250, v78, v79
	v_mov_b32_e32 v251, v250
	s_nop 1
	v_permlane32_swap_b32_e32 v250, v251
	s_waitcnt lgkmcnt(6)
	v_mfma_f32_32x32x16_bf16 v[16:31], v[166:169], v[220:223], v[16:31]
	ds_read_b64_tr_b16 v[220:221], v193 offset:0x1600
	ds_read_b64_tr_b16 v[222:223], v193 offset:0x1e00
	v_max_f32_e32 v251, v251, v251
	v_max_f32_e32 v250, v250, v250
	v_max_f32_e32 v250, v250, v251
	v_sub_f32_e32 v251, v250, v174
	v_cmp_ge_f32_e32 vcc, s93, v251
	s_waitcnt lgkmcnt(6)
	v_mfma_f32_32x32x16_bf16 v[16:31], v[170:173], v[224:227], v[16:31]
	ds_read_b64_tr_b16 v[224:225], v193 offset:0x2600
	ds_read_b64_tr_b16 v[226:227], v193 offset:0x2e00
	v_max_f32_e32 v251, v174, v174
	v_max_f32_e32 v250, v251, v250
	v_sub_f32_e32 v251, v174, v250
	v_mul_f32_e32 v251, 0x3e0293ee, v251
	s_waitcnt lgkmcnt(6)
	v_mfma_f32_32x32x16_bf16 v[16:31], v[212:215], v[232:235], v[16:31]
	ds_read_b64_tr_b16 v[232:233], v193 offset:0x3600
	ds_read_b64_tr_b16 v[234:235], v193 offset:0x3e00
	v_exp_f32_e32 v251, v251
	s_waitcnt lgkmcnt(6)
	v_mfma_f32_32x32x16_bf16 v[0:15], v[162:165], v[216:219], v[0:15]
	s_waitcnt lgkmcnt(4)
	v_mfma_f32_32x32x16_bf16 v[0:15], v[166:169], v[220:223], v[0:15]
	s_waitcnt lgkmcnt(2)
	v_mfma_f32_32x32x16_bf16 v[0:15], v[170:173], v[224:227], v[0:15]
	s_waitcnt lgkmcnt(0)
	v_mfma_f32_32x32x16_bf16 v[0:15], v[212:215], v[232:235], v[0:15]
	s_cmp_eq_u64 vcc, exec
	s_cselect_b64 s[6:7], -1, 0
	s_branch .Lgqa_joinA
.Lgqa_loopA:
	ds_read_b128 v[236:239], v200 offset:49152
	ds_read_b128 v[240:243], v208 offset:49152
	ds_read_b128 v[244:247], v207 offset:49152
	ds_read_b128 v[248:251], v206 offset:49152
	s_add_i32 s6, s14, -3
	s_waitcnt lgkmcnt(3)
	v_mfma_f32_32x32x16_bf16 v[80:95], v[236:239], v[124:127], 0
	ds_read_b128 v[236:239], v205 offset:49152
	v_exp_f32_e32 v162, v162
	v_exp_f32_e32 v216, v216
	v_pk_fma_f32 v[158:159], v[64:65], s[92:93], v[152:153] op_sel_hi:[1,0,0]
	s_waitcnt lgkmcnt(3)
	v_mfma_f32_32x32x16_bf16 v[80:95], v[240:243], v[120:123], v[80:95]
	ds_read_b128 v[240:243], v204 offset:49152
	v_exp_f32_e32 v163, v163
	v_exp_f32_e32 v177, v177
	v_pk_fma_f32 v[156:157], v[66:67], s[92:93], v[152:153] op_sel_hi:[1,0,0]
	s_waitcnt lgkmcnt(3)
	v_mfma_f32_32x32x16_bf16 v[80:95], v[244:247], v[116:119], v[80:95]
	ds_read_b128 v[244:247], v202 offset:49152
	v_exp_f32_e32 v164, v164
	v_exp_f32_e32 v176, v176
	v_pk_fma_f32 v[150:151], v[68:69], s[92:93], v[152:153] op_sel_hi:[1,0,0]
	s_waitcnt lgkmcnt(3)
	v_mfma_f32_32x32x16_bf16 v[80:95], v[248:251], v[112:115], v[80:95]
	ds_read_b128 v[248:251], v201 offset:49152
	v_exp_f32_e32 v165, v165
	v_exp_f32_e32 v175, v175
	v_pk_fma_f32 v[148:149], v[70:71], s[92:93], v[152:153] op_sel_hi:[1,0,0]
	s_waitcnt lgkmcnt(3)
	v_mfma_f32_32x32x16_bf16 v[80:95], v[236:239], v[108:111], v[80:95]
	ds_read_b128 v[236:239], v200 offset:57344
	v_exp_f32_e32 v166, v166
	v_exp_f32_e32 v173, v173
	v_pk_fma_f32 v[146:147], v[72:73], s[92:93], v[152:153] op_sel_hi:[1,0,0]
	s_waitcnt lgkmcnt(3)
	v_mfma_f32_32x32x16_bf16 v[80:95], v[240:243], v[104:107], v[80:95]
	ds_read_b128 v[240:243], v208 offset:57344
	v_exp_f32_e32 v167, v167
	v_exp_f32_e32 v172, v172
	v_pk_fma_f32 v[160:161], v[74:75], s[92:93], v[152:153] op_sel_hi:[1,0,0]
	s_waitcnt lgkmcnt(3)
	v_mfma_f32_32x32x16_bf16 v[80:95], v[244:247], v[100:103], v[80:95]
	ds_read_b128 v[244:247], v207 offset:57344
	v_exp_f32_e32 v168, v168
	v_exp_f32_e32 v171, v171
	v_pk_fma_f32 v[154:155], v[76:77], s[92:93], v[152:153] op_sel_hi:[1,0,0]
	s_waitcnt lgkmcnt(3)
	v_mfma_f32_32x32x16_bf16 v[80:95], v[248:251], v[96:99], v[80:95]
	ds_read_b128 v[248:251], v206 offset:57344
	v_exp_f32_e32 v169, v169
	v_exp_f32_e32 v170, v170
	v_pk_fma_f32 v[152:153], v[78:79], s[92:93], v[152:153] op_sel_hi:[1,0,0]
	s_waitcnt lgkmcnt(3)
	v_mfma_f32_32x32x16_bf16 v[64:79], v[236:239], v[124:127], 0
	ds_read_b128 v[236:239], v205 offset:57344
	v_exp_f32_e32 v158, v158
	v_exp_f32_e32 v159, v159
	v_add_f32_e32 v210, 0, v162
	s_waitcnt lgkmcnt(3)
	v_mfma_f32_32x32x16_bf16 v[64:79], v[240:243], v[120:123], v[64:79]
	ds_read_b128 v[240:243], v204 offset:57344
	v_exp_f32_e32 v156, v156
	v_exp_f32_e32 v157, v157
	v_add_f32_e32 v210, v216, v210
	s_waitcnt lgkmcnt(3)
	v_mfma_f32_32x32x16_bf16 v[64:79], v[244:247], v[116:119], v[64:79]
	ds_read_b128 v[244:247], v202 offset:57344
	v_exp_f32_e32 v150, v150
	v_exp_f32_e32 v151, v151
	v_add_f32_e32 v210, v163, v210
	s_waitcnt lgkmcnt(3)
	v_mfma_f32_32x32x16_bf16 v[64:79], v[248:251], v[112:115], v[64:79]
	ds_read_b128 v[248:251], v201 offset:57344
	v_exp_f32_e32 v148, v148
	v_exp_f32_e32 v149, v149
	v_add_f32_e32 v210, v177, v210
	s_waitcnt lgkmcnt(3)
	v_mfma_f32_32x32x16_bf16 v[64:79], v[236:239], v[108:111], v[64:79]
	v_exp_f32_e32 v146, v146
	v_exp_f32_e32 v147, v147
	v_add_f32_e32 v210, v164, v210
	s_waitcnt lgkmcnt(2)
	v_mfma_f32_32x32x16_bf16 v[64:79], v[240:243], v[104:107], v[64:79]
	v_exp_f32_e32 v160, v160
	v_exp_f32_e32 v161, v161
	v_add_f32_e32 v210, v176, v210
	s_waitcnt lgkmcnt(1)
	v_mfma_f32_32x32x16_bf16 v[64:79], v[244:247], v[100:103], v[64:79]
	v_exp_f32_e32 v154, v154
	v_exp_f32_e32 v155, v155
	v_add_f32_e32 v210, v165, v210
	s_waitcnt lgkmcnt(0)
	v_mfma_f32_32x32x16_bf16 v[64:79], v[248:251], v[96:99], v[64:79]
	v_exp_f32_e32 v152, v152
	v_exp_f32_e32 v153, v153
	v_add_f32_e32 v210, v175, v210
	s_waitcnt vmcnt(0)
	ds_write_b128 v198, v[136:139] offset:32768
	ds_write_b128 v199, v[140:143] offset:32768
	s_sub_i32 s7, s8, 64
	s_cmp_lt_u32 s6, 2
	s_cselect_b32 s6, s15, s7
	s_ashr_i32 s7, s6, 31
	v_cvt_pk_bf16_f32 v162, v162, v216
	v_cvt_pk_bf16_f32 v163, v163, v177
	v_cvt_pk_bf16_f32 v164, v164, v176
	v_cvt_pk_bf16_f32 v165, v165, v175
	s_nop 0
	v_permlane32_swap_b32_e32 v162, v164
	v_permlane32_swap_b32_e32 v163, v165
	ds_read_b64_tr_b16 v[216:217], v193 offset:0
	ds_read_b64_tr_b16 v[218:219], v193 offset:0x800
	s_waitcnt lgkmcnt(0)
	v_mfma_f32_32x32x16_bf16 v[48:63], v[162:165], v[216:219], v[48:63]
	ds_read_b64_tr_b16 v[220:221], v193 offset:0x1000
	ds_read_b64_tr_b16 v[222:223], v193 offset:0x1800
	ds_read_b64_tr_b16 v[224:225], v193 offset:0x2000
	ds_read_b64_tr_b16 v[226:227], v193 offset:0x2800
	ds_read_b64_tr_b16 v[232:233], v193 offset:0x3000
	ds_read_b64_tr_b16 v[234:235], v193 offset:0x3800
	ds_read_b64_tr_b16 v[216:217], v193 offset:0x200
	ds_read_b64_tr_b16 v[218:219], v193 offset:0xa00
	v_add_f32_e32 v210, v166, v210
	v_add_f32_e32 v210, v173, v210
	v_add_f32_e32 v210, v167, v210
	v_add_f32_e32 v210, v172, v210
	v_add_f32_e32 v210, v168, v210
	v_add_f32_e32 v210, v171, v210
	v_add_f32_e32 v210, v169, v210
	v_cvt_pk_bf16_f32 v166, v166, v173
	v_cvt_pk_bf16_f32 v167, v167, v172
	v_cvt_pk_bf16_f32 v168, v168, v171
	v_cvt_pk_bf16_f32 v169, v169, v170
	s_nop 0
	v_permlane32_swap_b32_e32 v166, v168
	v_permlane32_swap_b32_e32 v167, v169
	s_waitcnt lgkmcnt(6)
	s_nop 0
	v_mfma_f32_32x32x16_bf16 v[48:63], v[166:169], v[220:223], v[48:63]
	ds_read_b64_tr_b16 v[220:221], v193 offset:0x1200
	ds_read_b64_tr_b16 v[222:223], v193 offset:0x1a00
	v_add_f32_e32 v210, v170, v210
	v_add_f32_e32 v210, v158, v210
	v_add_f32_e32 v210, v159, v210
	v_add_f32_e32 v210, v156, v210
	v_add_f32_e32 v210, v157, v210
	v_cvt_pk_bf16_f32 v170, v158, v159
	v_cvt_pk_bf16_f32 v171, v156, v157
	v_cvt_pk_bf16_f32 v172, v150, v151
	v_cvt_pk_bf16_f32 v173, v148, v149
	s_nop 0
	v_permlane32_swap_b32_e32 v170, v172
	v_permlane32_swap_b32_e32 v171, v173
	s_waitcnt lgkmcnt(6)
	s_nop 0
	v_mfma_f32_32x32x16_bf16 v[48:63], v[170:173], v[224:227], v[48:63]
	ds_read_b64_tr_b16 v[224:225], v193 offset:0x2200
	ds_read_b64_tr_b16 v[226:227], v193 offset:0x2a00
	v_add_f32_e32 v210, v150, v210
	v_add_f32_e32 v210, v151, v210
	v_add_f32_e32 v210, v148, v210
	v_add_f32_e32 v210, v149, v210
	v_add_f32_e32 v210, v146, v210
	v_cvt_pk_bf16_f32 v212, v146, v147
	v_cvt_pk_bf16_f32 v213, v160, v161
	v_cvt_pk_bf16_f32 v214, v154, v155
	v_cvt_pk_bf16_f32 v215, v152, v153
	s_nop 0
	v_permlane32_swap_b32_e32 v212, v214
	v_permlane32_swap_b32_e32 v213, v215
	s_waitcnt lgkmcnt(6)
	s_nop 0
	v_mfma_f32_32x32x16_bf16 v[48:63], v[212:215], v[232:235], v[48:63]
	ds_read_b64_tr_b16 v[232:233], v193 offset:0x3200
	ds_read_b64_tr_b16 v[234:235], v193 offset:0x3a00
	v_add_f32_e32 v210, v147, v210
	v_add_f32_e32 v210, v160, v210
	v_add_f32_e32 v210, v161, v210
	v_add_f32_e32 v210, v154, v210
	v_add_f32_e32 v210, v155, v210
	s_waitcnt lgkmcnt(6)
	v_mfma_f32_32x32x16_bf16 v[32:47], v[162:165], v[216:219], v[32:47]
	ds_read_b64_tr_b16 v[216:217], v193 offset:0x400
	ds_read_b64_tr_b16 v[218:219], v193 offset:0xc00
	v_add_f32_e32 v210, v152, v210
	v_add_f32_e32 v210, v153, v210
	v_mov_b32_e32 v211, v210
	s_nop 1
	v_permlane32_swap_b32_e32 v210, v211
	v_lshl_add_u64 v[146:147], s[6:7], 0, v[178:179]
	s_waitcnt lgkmcnt(6)
	v_mfma_f32_32x32x16_bf16 v[32:47], v[166:169], v[220:223], v[32:47]
	ds_read_b64_tr_b16 v[220:221], v193 offset:0x1400
	ds_read_b64_tr_b16 v[222:223], v193 offset:0x1c00
	v_mul_lo_u32 v148, v147, s40
	v_mul_lo_u32 v149, v146, s41
	v_mad_u64_u32 v[146:147], s[10:11], v146, s40, 0
	v_add3_u32 v147, v147, v149, v148
	v_lshl_add_u64 v[148:149], v[180:181], 0, s[6:7]
	v_mul_lo_u32 v150, v149, s40
	v_mul_lo_u32 v151, v148, s41
	v_mad_u64_u32 v[148:149], s[6:7], v148, s40, 0
	v_add3_u32 v149, v149, v151, v150
	v_lshlrev_b64 v[154:155], 1, v[146:147]
	v_lshlrev_b64 v[156:157], 1, v[148:149]
	v_lshl_add_u64 v[146:147], v[182:183], 0, v[154:155]
	global_load_dwordx4 v[146:149], v[146:147], off
	v_lshl_add_u64 v[150:151], v[182:183], 0, v[156:157]
	global_load_dwordx4 v[150:153], v[150:151], off
	v_lshl_add_u64 v[154:155], v[184:185], 0, v[154:155]
	v_lshl_add_u64 v[158:159], v[184:185], 0, v[156:157]
	global_load_dwordx4 v[154:157], v[154:155], off
	global_load_dwordx4 v[158:161], v[158:159], off
	s_waitcnt lgkmcnt(6)
	v_mfma_f32_32x32x16_bf16 v[32:47], v[170:173], v[224:227], v[32:47]
	ds_read_b64_tr_b16 v[224:225], v193 offset:0x2400
	ds_read_b64_tr_b16 v[226:227], v193 offset:0x2c00
	v_max_f32_e32 v250, v81, v81
	v_max_f32_e32 v251, v80, v80
	v_max_f32_e32 v250, v251, v250
	v_max3_f32 v250, v250, v82, v83
	v_max3_f32 v250, v250, v84, v85
	s_waitcnt lgkmcnt(6)
	v_mfma_f32_32x32x16_bf16 v[32:47], v[212:215], v[232:235], v[32:47]
	ds_read_b64_tr_b16 v[232:233], v193 offset:0x3400
	ds_read_b64_tr_b16 v[234:235], v193 offset:0x3c00
	v_max3_f32 v250, v250, v86, v87
	v_max3_f32 v250, v250, v88, v89
	v_max3_f32 v250, v250, v90, v91
	v_max3_f32 v250, v250, v92, v93
	v_max3_f32 v250, v250, v94, v95
	s_waitcnt lgkmcnt(6)
	v_mfma_f32_32x32x16_bf16 v[16:31], v[162:165], v[216:219], v[16:31]
	ds_read_b64_tr_b16 v[216:217], v193 offset:0x600
	ds_read_b64_tr_b16 v[218:219], v193 offset:0xe00
	v_max3_f32 v250, v250, v64, v65
	v_max3_f32 v250, v250, v66, v67
	v_max3_f32 v250, v250, v68, v69
	v_max3_f32 v250, v250, v70, v71
	v_max3_f32 v250, v250, v72, v73
	s_waitcnt lgkmcnt(6)
	v_mfma_f32_32x32x16_bf16 v[16:31], v[166:169], v[220:223], v[16:31]
	ds_read_b64_tr_b16 v[220:221], v193 offset:0x1600
	ds_read_b64_tr_b16 v[222:223], v193 offset:0x1e00
	v_max3_f32 v250, v250, v74, v75
	v_max3_f32 v250, v250, v76, v77
	v_max3_f32 v250, v250, v78, v79
	v_mov_b32_e32 v251, v250
	s_nop 1
	v_permlane32_swap_b32_e32 v250, v251
	s_waitcnt lgkmcnt(6)
	v_mfma_f32_32x32x16_bf16 v[16:31], v[170:173], v[224:227], v[16:31]
	ds_read_b64_tr_b16 v[224:225], v193 offset:0x2600
	ds_read_b64_tr_b16 v[226:227], v193 offset:0x2e00
	v_max_f32_e32 v251, v251, v251
	v_max_f32_e32 v250, v250, v250
	v_max_f32_e32 v250, v250, v251
	v_sub_f32_e32 v251, v250, v174
	v_cmp_ge_f32_e32 vcc, s93, v251
	s_waitcnt lgkmcnt(6)
	v_mfma_f32_32x32x16_bf16 v[16:31], v[212:215], v[232:235], v[16:31]
	ds_read_b64_tr_b16 v[232:233], v193 offset:0x3600
	ds_read_b64_tr_b16 v[234:235], v193 offset:0x3e00
	v_max_f32_e32 v251, v174, v174
	v_max_f32_e32 v250, v251, v250
	v_sub_f32_e32 v251, v174, v250
	v_mul_f32_e32 v251, 0x3e0293ee, v251
	s_waitcnt lgkmcnt(6)
	v_mfma_f32_32x32x16_bf16 v[0:15], v[162:165], v[216:219], v[0:15]
	v_exp_f32_e32 v251, v251
	s_waitcnt lgkmcnt(4)
	v_mfma_f32_32x32x16_bf16 v[0:15], v[166:169], v[220:223], v[0:15]
	s_waitcnt lgkmcnt(2)
	v_mfma_f32_32x32x16_bf16 v[0:15], v[170:173], v[224:227], v[0:15]
	s_waitcnt lgkmcnt(0)
	v_mfma_f32_32x32x16_bf16 v[0:15], v[212:215], v[232:235], v[0:15]
	s_cmp_eq_u64 vcc, exec
	s_cselect_b64 s[6:7], -1, 0
.Lgqa_joinA:
	s_barrier
	v_cndmask_b32_e64 v217, v251, 1.0, s[6:7]
	v_cmp_gt_f32_e32 vcc, 1.0, v217
	ds_write_b128 v195, v[128:131]
	ds_write_b128 v196, v[132:135]
	s_cbranch_vccz .LBB0_743
	s_and_saveexec_b64 s[10:11], s[4:5]
	ds_write_b32 v194, v217 offset:128
	s_or_b64 exec, exec, s[10:11]
	s_waitcnt lgkmcnt(0)
	v_add_u32_e32 v163, v192, v144
	ds_read_b128 v[164:167], v163 offset:224
	ds_read_b128 v[168:171], v163 offset:192
	ds_read_b128 v[212:215], v163 offset:160
	ds_read_b128 v[218:221], v163 offset:128
	s_waitcnt lgkmcnt(3)
	v_pk_mul_f32 v[60:61], v[60:61], v[164:165]
	s_waitcnt lgkmcnt(2)
	v_pk_mul_f32 v[56:57], v[56:57], v[168:169]
	s_waitcnt lgkmcnt(1)
	v_pk_mul_f32 v[52:53], v[52:53], v[212:213]
	v_pk_mul_f32 v[62:63], v[62:63], v[166:167]
	v_pk_mul_f32 v[58:59], v[58:59], v[170:171]
	v_pk_mul_f32 v[54:55], v[54:55], v[214:215]
	s_waitcnt lgkmcnt(0)
	v_pk_mul_f32 v[50:51], v[50:51], v[220:221]
	v_pk_mul_f32 v[48:49], v[48:49], v[218:219]
	v_pk_mul_f32 v[44:45], v[44:45], v[164:165]
	v_pk_mul_f32 v[40:41], v[40:41], v[168:169]
	v_pk_mul_f32 v[36:37], v[36:37], v[212:213]
	v_pk_mul_f32 v[46:47], v[46:47], v[166:167]
	v_pk_mul_f32 v[42:43], v[42:43], v[170:171]
	v_pk_mul_f32 v[38:39], v[38:39], v[214:215]
	v_pk_mul_f32 v[34:35], v[34:35], v[220:221]
	v_pk_mul_f32 v[32:33], v[32:33], v[218:219]
	v_pk_mul_f32 v[28:29], v[28:29], v[164:165]
	v_pk_mul_f32 v[24:25], v[24:25], v[168:169]
	v_pk_mul_f32 v[20:21], v[20:21], v[212:213]
	v_pk_mul_f32 v[30:31], v[30:31], v[166:167]
	v_pk_mul_f32 v[26:27], v[26:27], v[170:171]
	v_pk_mul_f32 v[22:23], v[22:23], v[214:215]
	v_pk_mul_f32 v[18:19], v[18:19], v[220:221]
	v_pk_mul_f32 v[16:17], v[16:17], v[218:219]
	v_pk_mul_f32 v[12:13], v[12:13], v[164:165]
	v_pk_mul_f32 v[8:9], v[8:9], v[168:169]
	v_pk_mul_f32 v[4:5], v[4:5], v[212:213]
	v_pk_mul_f32 v[14:15], v[14:15], v[166:167]
	v_pk_mul_f32 v[10:11], v[10:11], v[170:171]
	v_pk_mul_f32 v[6:7], v[6:7], v[214:215]
	v_pk_mul_f32 v[2:3], v[2:3], v[220:221]
	v_pk_mul_f32 v[0:1], v[0:1], v[218:219]
.LBB0_743:
	v_cndmask_b32_e64 v216, v250, v174, s[6:7]
	v_mul_f32_e32 v212, 0xbe0293ee, v216
	v_fmamk_f32 v162, v80, 0x3e0293ee, v212
	v_fmamk_f32 v177, v81, 0x3e0293ee, v212
	v_fmamk_f32 v163, v82, 0x3e0293ee, v212
	v_fmamk_f32 v176, v83, 0x3e0293ee, v212
	v_fmamk_f32 v164, v84, 0x3e0293ee, v212
	v_fmamk_f32 v175, v85, 0x3e0293ee, v212
	v_fmamk_f32 v165, v86, 0x3e0293ee, v212
	v_fmamk_f32 v174, v87, 0x3e0293ee, v212
	v_fmamk_f32 v166, v88, 0x3e0293ee, v212
	v_fmamk_f32 v173, v89, 0x3e0293ee, v212
	v_fmamk_f32 v167, v90, 0x3e0293ee, v212
	v_fmamk_f32 v172, v91, 0x3e0293ee, v212
	v_fmamk_f32 v168, v92, 0x3e0293ee, v212
	v_fmamk_f32 v171, v93, 0x3e0293ee, v212
	v_fmamk_f32 v169, v94, 0x3e0293ee, v212
	v_fmamk_f32 v170, v95, 0x3e0293ee, v212
	ds_read_b128 v[240:243], v200 offset:32768
	ds_read_b128 v[244:247], v208 offset:32768
	ds_read_b128 v[248:251], v207 offset:32768
	s_waitcnt lgkmcnt(2)
	v_mfma_f32_32x32x16_bf16 v[80:95], v[240:243], v[124:127], 0
	ds_read_b128 v[240:243], v206 offset:32768
	v_exp_f32_e32 v162, v162
	v_exp_f32_e32 v177, v177
	v_fmamk_f32 v219, v70, 0x3e0293ee, v212
	s_waitcnt lgkmcnt(2)
	v_mfma_f32_32x32x16_bf16 v[80:95], v[244:247], v[120:123], v[80:95]
	ds_read_b128 v[244:247], v205 offset:32768
	v_exp_f32_e32 v163, v163
	v_exp_f32_e32 v176, v176
	v_fmamk_f32 v220, v71, 0x3e0293ee, v212
	s_waitcnt lgkmcnt(2)
	v_mfma_f32_32x32x16_bf16 v[80:95], v[248:251], v[116:119], v[80:95]
	ds_read_b128 v[248:251], v204 offset:32768
	v_exp_f32_e32 v164, v164
	v_exp_f32_e32 v175, v175
	v_fmamk_f32 v225, v64, 0x3e0293ee, v212
	s_waitcnt lgkmcnt(2)
	v_mfma_f32_32x32x16_bf16 v[80:95], v[240:243], v[112:115], v[80:95]
	ds_read_b128 v[240:243], v202 offset:32768
	v_exp_f32_e32 v165, v165
	v_exp_f32_e32 v174, v174
	v_fmamk_f32 v226, v65, 0x3e0293ee, v212
	s_waitcnt lgkmcnt(2)
	v_mfma_f32_32x32x16_bf16 v[80:95], v[244:247], v[108:111], v[80:95]
	ds_read_b128 v[244:247], v201 offset:32768
	v_exp_f32_e32 v166, v166
	v_exp_f32_e32 v173, v173
	v_fmamk_f32 v227, v66, 0x3e0293ee, v212
	s_waitcnt lgkmcnt(2)
	v_mfma_f32_32x32x16_bf16 v[80:95], v[248:251], v[104:107], v[80:95]
	ds_read_b128 v[248:251], v200 offset:40960
	v_exp_f32_e32 v167, v167
	v_exp_f32_e32 v172, v172
	v_fmamk_f32 v232, v67, 0x3e0293ee, v212
	s_waitcnt lgkmcnt(2)
	v_mfma_f32_32x32x16_bf16 v[80:95], v[240:243], v[100:103], v[80:95]
	ds_read_b128 v[240:243], v208 offset:40960
	v_exp_f32_e32 v168, v168
	v_exp_f32_e32 v171, v171
	v_fmamk_f32 v233, v68, 0x3e0293ee, v212
	s_waitcnt lgkmcnt(2)
	v_mfma_f32_32x32x16_bf16 v[80:95], v[244:247], v[96:99], v[80:95]
	ds_read_b128 v[244:247], v207 offset:40960
	v_exp_f32_e32 v169, v169
	v_exp_f32_e32 v170, v170
	v_fmamk_f32 v218, v69, 0x3e0293ee, v212
	v_fmamk_f32 v221, v72, 0x3e0293ee, v212
	v_fmamk_f32 v222, v73, 0x3e0293ee, v212
	v_fmamk_f32 v223, v74, 0x3e0293ee, v212
	v_fmamk_f32 v224, v75, 0x3e0293ee, v212
	v_fmamk_f32 v213, v76, 0x3e0293ee, v212
	v_fmamk_f32 v234, v77, 0x3e0293ee, v212
	v_fmamk_f32 v235, v78, 0x3e0293ee, v212
	v_fmac_f32_e32 v212, 0x3e0293ee, v79
	s_waitcnt lgkmcnt(2)
	v_mfma_f32_32x32x16_bf16 v[64:79], v[248:251], v[124:127], 0
	ds_read_b128 v[248:251], v206 offset:40960
	v_exp_f32_e32 v215, v226
	v_exp_f32_e32 v226, v232
	s_waitcnt lgkmcnt(2)
	v_mfma_f32_32x32x16_bf16 v[64:79], v[240:243], v[120:123], v[64:79]
	ds_read_b128 v[240:243], v205 offset:40960
	v_exp_f32_e32 v232, v219
	v_add_f32_e32 v219, 0, v162
	v_add_f32_e32 v219, v177, v219
	v_add_f32_e32 v219, v163, v219
	s_waitcnt lgkmcnt(2)
	v_mfma_f32_32x32x16_bf16 v[64:79], v[244:247], v[116:119], v[64:79]
	ds_read_b128 v[244:247], v204 offset:40960
	v_add_f32_e32 v219, v176, v219
	v_add_f32_e32 v219, v164, v219
	v_add_f32_e32 v219, v175, v219
	v_add_f32_e32 v219, v165, v219
	v_add_f32_e32 v219, v174, v219
	s_waitcnt lgkmcnt(2)
	v_mfma_f32_32x32x16_bf16 v[64:79], v[248:251], v[112:115], v[64:79]
	ds_read_b128 v[248:251], v202 offset:40960
	v_add_f32_e32 v219, v166, v219
	v_add_f32_e32 v219, v173, v219
	v_add_f32_e32 v219, v167, v219
	v_add_f32_e32 v219, v172, v219
	v_add_f32_e32 v219, v168, v219
	s_waitcnt lgkmcnt(2)
	v_mfma_f32_32x32x16_bf16 v[64:79], v[240:243], v[108:111], v[64:79]
	ds_read_b128 v[240:243], v201 offset:40960
	v_exp_f32_e32 v214, v225
	v_add_f32_e32 v219, v171, v219
	v_exp_f32_e32 v225, v227
	s_waitcnt lgkmcnt(2)
	v_mfma_f32_32x32x16_bf16 v[64:79], v[244:247], v[104:107], v[64:79]
	v_add_f32_e32 v219, v169, v219
	v_add_f32_e32 v219, v170, v219
	v_exp_f32_e32 v227, v233
	v_add_f32_e32 v219, v214, v219
	s_waitcnt lgkmcnt(1)
	v_mfma_f32_32x32x16_bf16 v[64:79], v[248:251], v[100:103], v[64:79]
	v_exp_f32_e32 v218, v218
	v_add_f32_e32 v219, v215, v219
	v_add_f32_e32 v219, v225, v219
	v_add_f32_e32 v219, v226, v219
	s_waitcnt lgkmcnt(0)
	v_mfma_f32_32x32x16_bf16 v[64:79], v[240:243], v[96:99], v[64:79]
	v_exp_f32_e32 v233, v220
	v_exp_f32_e32 v221, v221
	v_add_f32_e32 v219, v227, v219
	s_cmp_ge_u32 s14, s91
	s_cselect_b64 s[10:11], -1, 0
	s_waitcnt vmcnt(0)
	ds_write_b128 v198, v[154:157] offset:49152
	ds_write_b128 v199, v[158:161] offset:49152
	s_ashr_i32 s9, s8, 31
	v_exp_f32_e32 v222, v222
	v_add_f32_e32 v219, v218, v219
	v_exp_f32_e32 v223, v223
	v_add_f32_e32 v219, v232, v219
	v_exp_f32_e32 v224, v224
	v_add_f32_e32 v219, v233, v219
	v_exp_f32_e32 v213, v213
	v_add_f32_e32 v219, v221, v219
	v_exp_f32_e32 v234, v234
	v_add_f32_e32 v219, v222, v219
	v_exp_f32_e32 v235, v235
	v_add_f32_e32 v219, v223, v219
	v_exp_f32_e32 v212, v212
	v_add_f32_e32 v219, v224, v219
	v_add_f32_e32 v219, v213, v219
	v_add_f32_e32 v219, v234, v219
	v_add_f32_e32 v219, v235, v219
	v_add_f32_e32 v219, v212, v219
	v_cvt_pk_bf16_f32 v162, v162, v177
	v_cvt_pk_bf16_f32 v163, v163, v176
	v_cvt_pk_bf16_f32 v164, v164, v175
	v_cvt_pk_bf16_f32 v165, v165, v174
	v_cvt_pk_bf16_f32 v169, v169, v170
	v_cvt_pk_bf16_f32 v170, v214, v215
	v_cvt_pk_bf16_f32 v176, v213, v234
	v_cvt_pk_bf16_f32 v177, v235, v212
	v_permlane32_swap_b32_e32 v162, v164
	v_permlane32_swap_b32_e32 v163, v165
	ds_read_b64_tr_b16 v[212:213], v197 offset:0
	ds_read_b64_tr_b16 v[214:215], v197 offset:0x800
	s_waitcnt lgkmcnt(0)
	v_mfma_f32_32x32x16_bf16 v[48:63], v[162:165], v[212:215], v[48:63]
	v_mov_b32_e32 v220, v219
	s_nop 1
	v_permlane32_swap_b32_e32 v219, v220
	v_cvt_pk_bf16_f32 v166, v166, v173
	v_cvt_pk_bf16_f32 v167, v167, v172
	v_cvt_pk_bf16_f32 v168, v168, v171
	v_cvt_pk_bf16_f32 v171, v225, v226
	v_cvt_pk_bf16_f32 v174, v221, v222
	v_cvt_pk_bf16_f32 v175, v223, v224
	v_permlane32_swap_b32_e32 v166, v168
	v_permlane32_swap_b32_e32 v167, v169
	ds_read_b64_tr_b16 v[222:223], v197 offset:0x1000
	ds_read_b64_tr_b16 v[224:225], v197 offset:0x1800
	s_waitcnt lgkmcnt(0)
	v_mfma_f32_32x32x16_bf16 v[48:63], v[166:169], v[222:225], v[48:63]
	v_cvt_pk_bf16_f32 v172, v227, v218
	v_cvt_pk_bf16_f32 v173, v232, v233
	s_nop 0
	v_permlane32_swap_b32_e32 v170, v172
	v_permlane32_swap_b32_e32 v171, v173
	v_permlane32_swap_b32_e32 v174, v176
	ds_read_b64_tr_b16 v[232:233], v197 offset:0x2000
	ds_read_b64_tr_b16 v[234:235], v197 offset:0x2800
	ds_read_b64_tr_b16 v[236:237], v197 offset:0x3000
	ds_read_b64_tr_b16 v[238:239], v197 offset:0x3800
	ds_read_b64_tr_b16 v[212:213], v197 offset:0x200
	ds_read_b64_tr_b16 v[214:215], v197 offset:0xa00
	ds_read_b64_tr_b16 v[222:223], v197 offset:0x1200
	ds_read_b64_tr_b16 v[224:225], v197 offset:0x1a00
	s_waitcnt lgkmcnt(6)
	v_mfma_f32_32x32x16_bf16 v[48:63], v[170:173], v[232:235], v[48:63]
	ds_read_b64_tr_b16 v[232:233], v197 offset:0x2200
	ds_read_b64_tr_b16 v[234:235], v197 offset:0x2a00
	v_permlane32_swap_b32_e32 v175, v177
	v_lshl_add_u64 v[128:129], s[8:9], 0, v[178:179]
	v_mul_lo_u32 v130, v129, s40
	v_mul_lo_u32 v131, v128, s41
	v_mad_u64_u32 v[128:129], s[6:7], v128, s40, 0
	s_waitcnt lgkmcnt(6)
	v_mfma_f32_32x32x16_bf16 v[48:63], v[174:177], v[236:239], v[48:63]
	ds_read_b64_tr_b16 v[236:237], v197 offset:0x3200
	ds_read_b64_tr_b16 v[238:239], v197 offset:0x3a00
	v_add3_u32 v129, v129, v131, v130
	v_lshl_add_u64 v[130:131], v[180:181], 0, s[8:9]
	v_mul_lo_u32 v132, v131, s40
	v_mul_lo_u32 v133, v130, s41
	v_mad_u64_u32 v[130:131], s[6:7], v130, s40, 0
	s_waitcnt lgkmcnt(6)
	v_mfma_f32_32x32x16_bf16 v[32:47], v[162:165], v[212:215], v[32:47]
	ds_read_b64_tr_b16 v[212:213], v197 offset:0x400
	ds_read_b64_tr_b16 v[214:215], v197 offset:0xc00
	v_add3_u32 v131, v131, v133, v132
	v_lshlrev_b64 v[136:137], 1, v[128:129]
	v_lshlrev_b64 v[138:139], 1, v[130:131]
	v_lshl_add_u64 v[128:129], v[182:183], 0, v[136:137]
	v_lshl_add_u64 v[132:133], v[182:183], 0, v[138:139]
	s_waitcnt lgkmcnt(6)
	v_mfma_f32_32x32x16_bf16 v[32:47], v[166:169], v[222:225], v[32:47]
	ds_read_b64_tr_b16 v[222:223], v197 offset:0x1400
	ds_read_b64_tr_b16 v[224:225], v197 offset:0x1c00
	v_lshl_add_u64 v[136:137], v[184:185], 0, v[136:137]
	v_lshl_add_u64 v[140:141], v[184:185], 0, v[138:139]
	v_max_f32_e32 v250, v81, v81
	v_max_f32_e32 v251, v80, v80
	v_max_f32_e32 v250, v251, v250
	global_load_dwordx4 v[128:131], v[128:129], off
	global_load_dwordx4 v[132:135], v[132:133], off
	global_load_dwordx4 v[136:139], v[136:137], off
	global_load_dwordx4 v[140:143], v[140:141], off
	s_waitcnt lgkmcnt(6)
	v_mfma_f32_32x32x16_bf16 v[32:47], v[170:173], v[232:235], v[32:47]
	ds_read_b64_tr_b16 v[232:233], v197 offset:0x2400
	ds_read_b64_tr_b16 v[234:235], v197 offset:0x2c00
	v_max3_f32 v250, v250, v82, v83
	v_max3_f32 v250, v250, v84, v85
	v_max3_f32 v250, v250, v86, v87
	v_max3_f32 v250, v250, v88, v89
	v_max3_f32 v250, v250, v90, v91
	s_waitcnt lgkmcnt(6)
	v_mfma_f32_32x32x16_bf16 v[32:47], v[174:177], v[236:239], v[32:47]
	ds_read_b64_tr_b16 v[236:237], v197 offset:0x3400
	ds_read_b64_tr_b16 v[238:239], v197 offset:0x3c00
	v_max3_f32 v250, v250, v92, v93
	v_max3_f32 v250, v250, v94, v95
	v_max3_f32 v250, v250, v64, v65
	v_max3_f32 v250, v250, v66, v67
	v_max3_f32 v250, v250, v68, v69
	s_waitcnt lgkmcnt(6)
	v_mfma_f32_32x32x16_bf16 v[16:31], v[162:165], v[212:215], v[16:31]
	ds_read_b64_tr_b16 v[212:213], v197 offset:0x600
	ds_read_b64_tr_b16 v[214:215], v197 offset:0xe00
	v_max3_f32 v250, v250, v70, v71
	v_max3_f32 v250, v250, v72, v73
	v_max3_f32 v250, v250, v74, v75
	v_max3_f32 v250, v250, v76, v77
	v_max3_f32 v250, v250, v78, v79
	s_waitcnt lgkmcnt(6)
	v_mfma_f32_32x32x16_bf16 v[16:31], v[166:169], v[222:225], v[16:31]
	ds_read_b64_tr_b16 v[222:223], v197 offset:0x1600
	ds_read_b64_tr_b16 v[224:225], v197 offset:0x1e00
	v_mov_b32_e32 v251, v250
	s_nop 1
	v_permlane32_swap_b32_e32 v250, v251
	v_max_f32_e32 v251, v251, v251
	v_max_f32_e32 v250, v250, v250
	v_max_f32_e32 v250, v250, v251
	s_waitcnt lgkmcnt(6)
	v_mfma_f32_32x32x16_bf16 v[16:31], v[170:173], v[232:235], v[16:31]
	ds_read_b64_tr_b16 v[232:233], v197 offset:0x2600
	ds_read_b64_tr_b16 v[234:235], v197 offset:0x2e00
	v_sub_f32_e32 v251, v250, v216
	v_cmp_ge_f32_e32 vcc, s93, v251
	v_max_f32_e32 v251, v216, v216
	v_max_f32_e32 v250, v251, v250
	v_sub_f32_e32 v251, v216, v250
	s_waitcnt lgkmcnt(6)
	v_mfma_f32_32x32x16_bf16 v[16:31], v[174:177], v[236:239], v[16:31]
	ds_read_b64_tr_b16 v[236:237], v197 offset:0x3600
	ds_read_b64_tr_b16 v[238:239], v197 offset:0x3e00
	v_mul_f32_e32 v251, 0x3e0293ee, v251
	v_exp_f32_e32 v251, v251
	s_waitcnt lgkmcnt(6)
	v_mfma_f32_32x32x16_bf16 v[0:15], v[162:165], v[212:215], v[0:15]
	s_waitcnt lgkmcnt(4)
	v_mfma_f32_32x32x16_bf16 v[0:15], v[166:169], v[222:225], v[0:15]
	s_waitcnt lgkmcnt(2)
	v_mfma_f32_32x32x16_bf16 v[0:15], v[170:173], v[232:235], v[0:15]
	s_waitcnt lgkmcnt(0)
	v_mfma_f32_32x32x16_bf16 v[0:15], v[174:177], v[236:239], v[0:15]
	s_cmp_eq_u64 vcc, exec
	s_cselect_b64 s[6:7], -1, 0
	s_barrier
	v_cndmask_b32_e64 v218, v251, 1.0, s[6:7]
	v_cmp_gt_f32_e32 vcc, 1.0, v218
	ds_write_b128 v195, v[146:149] offset:16384
	ds_write_b128 v196, v[150:153] offset:16384
	s_cbranch_vccz .LBB0_749
	s_and_saveexec_b64 s[12:13], s[4:5]
	ds_write_b32 v194, v218 offset:128
	s_or_b64 exec, exec, s[12:13]
	s_waitcnt lgkmcnt(0)
	v_add_u32_e32 v158, v192, v144
	ds_read_b128 v[146:149], v158 offset:224
	ds_read_b128 v[150:153], v158 offset:192
	ds_read_b128 v[154:157], v158 offset:160
	ds_read_b128 v[158:161], v158 offset:128
	s_waitcnt lgkmcnt(3)
	v_pk_mul_f32 v[60:61], v[60:61], v[146:147]
	s_waitcnt lgkmcnt(2)
	v_pk_mul_f32 v[56:57], v[56:57], v[150:151]
	s_waitcnt lgkmcnt(1)
	v_pk_mul_f32 v[52:53], v[52:53], v[154:155]
	v_pk_mul_f32 v[62:63], v[62:63], v[148:149]
	v_pk_mul_f32 v[58:59], v[58:59], v[152:153]
	v_pk_mul_f32 v[54:55], v[54:55], v[156:157]
	s_waitcnt lgkmcnt(0)
	v_pk_mul_f32 v[50:51], v[50:51], v[160:161]
	v_pk_mul_f32 v[48:49], v[48:49], v[158:159]
	v_pk_mul_f32 v[44:45], v[44:45], v[146:147]
	v_pk_mul_f32 v[40:41], v[40:41], v[150:151]
	v_pk_mul_f32 v[36:37], v[36:37], v[154:155]
	v_pk_mul_f32 v[46:47], v[46:47], v[148:149]
	v_pk_mul_f32 v[42:43], v[42:43], v[152:153]
	v_pk_mul_f32 v[38:39], v[38:39], v[156:157]
	v_pk_mul_f32 v[34:35], v[34:35], v[160:161]
	v_pk_mul_f32 v[32:33], v[32:33], v[158:159]
	v_pk_mul_f32 v[28:29], v[28:29], v[146:147]
	v_pk_mul_f32 v[24:25], v[24:25], v[150:151]
	v_pk_mul_f32 v[20:21], v[20:21], v[154:155]
	v_pk_mul_f32 v[30:31], v[30:31], v[148:149]
	v_pk_mul_f32 v[26:27], v[26:27], v[152:153]
	v_pk_mul_f32 v[22:23], v[22:23], v[156:157]
	v_pk_mul_f32 v[18:19], v[18:19], v[160:161]
	v_pk_mul_f32 v[16:17], v[16:17], v[158:159]
	v_pk_mul_f32 v[12:13], v[12:13], v[146:147]
	v_pk_mul_f32 v[8:9], v[8:9], v[150:151]
	v_pk_mul_f32 v[4:5], v[4:5], v[154:155]
	v_pk_mul_f32 v[14:15], v[14:15], v[148:149]
	v_pk_mul_f32 v[10:11], v[10:11], v[152:153]
	v_pk_mul_f32 v[6:7], v[6:7], v[156:157]
	v_pk_mul_f32 v[2:3], v[2:3], v[160:161]
	v_pk_mul_f32 v[0:1], v[0:1], v[158:159]
.LBB0_749:
	v_cndmask_b32_e64 v174, v250, v216, s[6:7]
	v_mul_f32_e32 v152, 0xbe0293ee, v174
	v_mov_b32_e32 v153, v152
	v_fmamk_f32 v162, v80, 0x3e0293ee, v152
	v_fmamk_f32 v216, v81, 0x3e0293ee, v152
	v_fmamk_f32 v163, v82, 0x3e0293ee, v152
	v_fmamk_f32 v177, v83, 0x3e0293ee, v152
	v_fmamk_f32 v164, v84, 0x3e0293ee, v152
	v_fmamk_f32 v176, v85, 0x3e0293ee, v152
	v_fmamk_f32 v165, v86, 0x3e0293ee, v152
	v_fmamk_f32 v175, v87, 0x3e0293ee, v152
	v_fmamk_f32 v166, v88, 0x3e0293ee, v152
	v_fmamk_f32 v173, v89, 0x3e0293ee, v152
	v_fmamk_f32 v167, v90, 0x3e0293ee, v152
	v_fmamk_f32 v172, v91, 0x3e0293ee, v152
	v_fmamk_f32 v168, v92, 0x3e0293ee, v152
	v_fmamk_f32 v171, v93, 0x3e0293ee, v152
	v_fmamk_f32 v169, v94, 0x3e0293ee, v152
	v_fmamk_f32 v170, v95, 0x3e0293ee, v152
	v_add_f32_e32 v252, v210, v211
	v_fmac_f32_e32 v252, v209, v203
	v_add_f32_e32 v203, v219, v220
	v_fmac_f32_e32 v203, v252, v217
	s_add_i32 s14, s14, 2
	s_addk_i32 s8, 0x80
	s_addk_i32 s15, 0x80
	s_and_b64 vcc, exec, s[10:11]
	s_cbranch_vccnz .Lgqa_exit
	v_mov_b32_e32 v209, v218
	s_branch .Lgqa_loopA
.Lgqa_exit:
	v_exp_f32_e32 v162, v162
	v_exp_f32_e32 v216, v216
	v_exp_f32_e32 v163, v163
	v_exp_f32_e32 v177, v177
	v_exp_f32_e32 v164, v164
	v_exp_f32_e32 v176, v176
	v_exp_f32_e32 v165, v165
	v_exp_f32_e32 v175, v175
	v_exp_f32_e32 v166, v166
	v_exp_f32_e32 v173, v173
	v_exp_f32_e32 v167, v167
	v_exp_f32_e32 v172, v172
	v_exp_f32_e32 v168, v168
	v_exp_f32_e32 v171, v171
	v_exp_f32_e32 v169, v169
	v_exp_f32_e32 v170, v170
	v_pk_fma_f32 v[158:159], v[64:65], s[92:93], v[152:153] op_sel_hi:[1,0,0]
	v_pk_fma_f32 v[156:157], v[66:67], s[92:93], v[152:153] op_sel_hi:[1,0,0]
	v_pk_fma_f32 v[150:151], v[68:69], s[92:93], v[152:153] op_sel_hi:[1,0,0]
	v_pk_fma_f32 v[148:149], v[70:71], s[92:93], v[152:153] op_sel_hi:[1,0,0]
	v_pk_fma_f32 v[146:147], v[72:73], s[92:93], v[152:153] op_sel_hi:[1,0,0]
	v_pk_fma_f32 v[160:161], v[74:75], s[92:93], v[152:153] op_sel_hi:[1,0,0]
	v_pk_fma_f32 v[154:155], v[76:77], s[92:93], v[152:153] op_sel_hi:[1,0,0]
	v_pk_fma_f32 v[152:153], v[78:79], s[92:93], v[152:153] op_sel_hi:[1,0,0]
